# diff-attn loop: next MFMA phase address setup + first LDS ring reads issued before the preceding softmax phase (separate softmax temporaries)
# speedup vs baseline: 1.0517x; 1.0109x over previous
.Ldv_pre_top:
	v_exp_f32_e32 v238, v98
	v_exp_f32_e32 v222, v82
	v_exp_f32_e32 v239, v99
	v_exp_f32_e32 v223, v83
	v_exp_f32_e32 v240, v100
	v_add_f32_e32 v196, v238, v239
	v_exp_f32_e32 v224, v84
	v_add_f32_e32 v198, v222, v223
	v_exp_f32_e32 v241, v101
	v_add_f32_e32 v196, v240, v196
	v_exp_f32_e32 v225, v85
	v_add_f32_e32 v198, v224, v198
	v_exp_f32_e32 v242, v102
	v_add_f32_e32 v196, v241, v196
	v_exp_f32_e32 v226, v86
	v_add_f32_e32 v198, v225, v198
	v_exp_f32_e32 v243, v103
	v_add_f32_e32 v196, v242, v196
	v_exp_f32_e32 v227, v87
	v_add_f32_e32 v198, v226, v198
	v_exp_f32_e32 v244, v104
	v_add_f32_e32 v196, v243, v196
	v_exp_f32_e32 v228, v88
	v_add_f32_e32 v198, v227, v198
	v_exp_f32_e32 v245, v105
	v_add_f32_e32 v196, v244, v196
	v_exp_f32_e32 v229, v89
	v_add_f32_e32 v198, v228, v198
	v_exp_f32_e32 v246, v106
	v_add_f32_e32 v196, v245, v196
	v_exp_f32_e32 v230, v90
	v_add_f32_e32 v198, v229, v198
	v_exp_f32_e32 v247, v107
	v_add_f32_e32 v196, v246, v196
	v_exp_f32_e32 v231, v91
	v_add_f32_e32 v198, v230, v198
	v_exp_f32_e32 v248, v108
	v_add_f32_e32 v196, v247, v196
	v_exp_f32_e32 v232, v92
	v_add_f32_e32 v198, v231, v198
	v_exp_f32_e32 v249, v109
	v_add_f32_e32 v196, v248, v196
	v_exp_f32_e32 v233, v93
	v_add_f32_e32 v198, v232, v198
	v_exp_f32_e32 v180, v110
	v_add_f32_e32 v196, v249, v196
	v_exp_f32_e32 v234, v94
	v_add_f32_e32 v198, v233, v198
	v_exp_f32_e32 v181, v111
	v_add_f32_e32 v196, v180, v196
	v_exp_f32_e32 v235, v95
	v_add_f32_e32 v198, v234, v198
	v_exp_f32_e32 v182, v112
	v_add_f32_e32 v196, v181, v196
	v_exp_f32_e32 v236, v96
	v_add_f32_e32 v198, v235, v198
	v_exp_f32_e32 v183, v113
	v_add_f32_e32 v196, v182, v196
	v_exp_f32_e32 v237, v97
	v_add_f32_e32 v198, v236, v198
	v_add_f32_e32 v196, v183, v196
	v_add_f32_e32 v198, v237, v198
	v_add_f32_e32 v199, v196, v198
	s_nop 0
	v_cmp_ngt_f32_e32 vcc, s72, v199
	s_nop 1
	s_or_b64 vcc, vcc, s[6:7]
	s_andn2_b64 vcc, vcc, s[8:9]
	s_cbranch_vccz .Ldv_pre_fast
	v_max3_f32 v221, v98, v99, v100
	v_max3_f32 v221, v221, v101, v102
	v_max3_f32 v221, v221, v103, v104
	v_max3_f32 v221, v221, v105, v106
	v_max3_f32 v221, v221, v107, v108
	v_max3_f32 v221, v221, v109, v110
	v_max3_f32 v221, v221, v111, v112
	v_max3_f32 v221, v221, v113, v82
	v_max3_f32 v221, v221, v83, v84
	v_max3_f32 v221, v221, v85, v86
	v_max3_f32 v221, v221, v87, v88
	v_max3_f32 v221, v221, v89, v90
	v_max3_f32 v221, v221, v91, v92
	v_max3_f32 v221, v221, v93, v94
	v_max3_f32 v221, v221, v95, v96
	v_max_f32_e32 v221, v221, v97
	ds_bpermute_b32 v162, v173, v221
	s_waitcnt lgkmcnt(0)
	v_max_f32_e32 v221, v221, v162
	s_and_b64 vcc, exec, s[6:7]
	s_cbranch_vccnz .Ldv_pre_anchor
	v_max_f32_e32 v221, 0, v221
	v_exp_f32_e64 v163, -v221
	s_nop 7
	s_nop 7
	v_mul_f32_e32 v197, v197, v163
	v_mul_f32_e32 v2, v2, v163
	v_mul_f32_e32 v3, v3, v163
	v_mul_f32_e32 v4, v4, v163
	v_mul_f32_e32 v5, v5, v163
	v_mul_f32_e32 v6, v6, v163
	v_mul_f32_e32 v7, v7, v163
	v_mul_f32_e32 v8, v8, v163
	v_mul_f32_e32 v9, v9, v163
	v_mul_f32_e32 v10, v10, v163
	v_mul_f32_e32 v11, v11, v163
	v_mul_f32_e32 v12, v12, v163
	v_mul_f32_e32 v13, v13, v163
	v_mul_f32_e32 v14, v14, v163
	v_mul_f32_e32 v15, v15, v163
	v_mul_f32_e32 v16, v16, v163
	v_mul_f32_e32 v17, v17, v163
	v_mul_f32_e32 v50, v50, v163
	v_mul_f32_e32 v51, v51, v163
	v_mul_f32_e32 v52, v52, v163
	v_mul_f32_e32 v53, v53, v163
	v_mul_f32_e32 v54, v54, v163
	v_mul_f32_e32 v55, v55, v163
	v_mul_f32_e32 v56, v56, v163
	v_mul_f32_e32 v57, v57, v163
	v_mul_f32_e32 v58, v58, v163
	v_mul_f32_e32 v59, v59, v163
	v_mul_f32_e32 v60, v60, v163
	v_mul_f32_e32 v61, v61, v163
	v_mul_f32_e32 v62, v62, v163
	v_mul_f32_e32 v63, v63, v163
	v_mul_f32_e32 v64, v64, v163
	v_mul_f32_e32 v65, v65, v163
	v_mul_f32_e32 v34, v34, v163
	v_mul_f32_e32 v35, v35, v163
	v_mul_f32_e32 v36, v36, v163
	v_mul_f32_e32 v37, v37, v163
	v_mul_f32_e32 v38, v38, v163
	v_mul_f32_e32 v39, v39, v163
	v_mul_f32_e32 v40, v40, v163
	v_mul_f32_e32 v41, v41, v163
	v_mul_f32_e32 v42, v42, v163
	v_mul_f32_e32 v43, v43, v163
	v_mul_f32_e32 v44, v44, v163
	v_mul_f32_e32 v45, v45, v163
	v_mul_f32_e32 v46, v46, v163
	v_mul_f32_e32 v47, v47, v163
	v_mul_f32_e32 v48, v48, v163
	v_mul_f32_e32 v49, v49, v163
	v_mul_f32_e32 v18, v18, v163
	v_mul_f32_e32 v19, v19, v163
	v_mul_f32_e32 v20, v20, v163
	v_mul_f32_e32 v21, v21, v163
	v_mul_f32_e32 v22, v22, v163
	v_mul_f32_e32 v23, v23, v163
	v_mul_f32_e32 v24, v24, v163
	v_mul_f32_e32 v25, v25, v163
	v_mul_f32_e32 v26, v26, v163
	v_mul_f32_e32 v27, v27, v163
	v_mul_f32_e32 v28, v28, v163
	v_mul_f32_e32 v29, v29, v163
	v_mul_f32_e32 v30, v30, v163
	v_mul_f32_e32 v31, v31, v163
	v_mul_f32_e32 v32, v32, v163
	v_mul_f32_e32 v33, v33, v163

.Ldv_pre_fast:
	v_cvt_pk_bf16_f32 v114, v238, v239
	v_cvt_pk_bf16_f32 v115, v240, v241
	v_cvt_pk_bf16_f32 v116, v242, v243
	v_cvt_pk_bf16_f32 v117, v244, v245
	v_cvt_pk_bf16_f32 v118, v246, v247
	v_cvt_pk_bf16_f32 v119, v248, v249
	v_cvt_pk_bf16_f32 v120, v180, v181
	v_cvt_pk_bf16_f32 v121, v182, v183
	v_cvt_pk_bf16_f32 v122, v222, v223
	v_cvt_pk_bf16_f32 v123, v224, v225
	v_cvt_pk_bf16_f32 v124, v226, v227
	v_cvt_pk_bf16_f32 v125, v228, v229
	v_cvt_pk_bf16_f32 v126, v230, v231
	v_cvt_pk_bf16_f32 v127, v232, v233
	v_cvt_pk_bf16_f32 v128, v234, v235
	v_cvt_pk_bf16_f32 v129, v236, v237
	v_add_f32_e32 v197, v197, v199

.Ldk_skip2:
	v_lshl_add_u32 v196, s11, 13, v211
	s_add_i32 s0, s40, 0xffff8000
	s_and_b32 s0, s0, 0x8000
	v_add_u32_e32 v221, s0, v216
	v_add_u32_e32 v162, v196, v212
	v_add_u32_e32 v163, v196, v213
	v_add_u32_e32 v164, v196, v214
	v_add_u32_e32 v165, v196, v215
	v_add_u32_e32 v166, v221, v217
	v_add_u32_e32 v167, v221, v218
	v_add_u32_e32 v168, v221, v219
	v_add_u32_e32 v169, v221, v220
	ds_read_b128 v[130:133], v162
	ds_read_b128 v[134:137], v162 offset:4096
	ds_read_b128 v[138:141], v163
	ds_read_b128 v[142:145], v163 offset:4096
	v_readlane_b32 s0, v252, 7
	s_cmpk_lt_u32 s0, 0x100
	s_cbranch_scc1 .Ldtop_skip
	s_cmp_eq_u32 s41, 2
	s_cselect_b64 s[6:7], -1, 0
	s_mov_b64 s[8:9], 0

.Ldtop_skip:
	s_setprio 1
	s_waitcnt lgkmcnt(3)
	v_mfma_f32_32x32x16_bf16 v[98:113], v[130:133], v[146:149], v[66:81]
	ds_read_b128 v[130:133], v164
	s_waitcnt lgkmcnt(3)
	v_mfma_f32_32x32x16_bf16 v[82:97], v[134:137], v[146:149], v[66:81]
	ds_read_b128 v[134:137], v164 offset:4096
	s_waitcnt lgkmcnt(3)
	v_mfma_f32_32x32x16_bf16 v[98:113], v[138:141], v[150:153], v[98:113]
	ds_read_b128 v[138:141], v165
	s_waitcnt lgkmcnt(3)
	v_mfma_f32_32x32x16_bf16 v[82:97], v[142:145], v[150:153], v[82:97]
	ds_read_b128 v[142:145], v165 offset:4096
	s_waitcnt lgkmcnt(3)
	v_mfma_f32_32x32x16_bf16 v[98:113], v[130:133], v[154:157], v[98:113]
	ds_read_b128 v[130:133], v166 offset:32768
	s_waitcnt lgkmcnt(3)
	v_mfma_f32_32x32x16_bf16 v[82:97], v[134:137], v[154:157], v[82:97]
	ds_read_b128 v[134:137], v166 offset:36864
	s_waitcnt lgkmcnt(3)
	v_mfma_f32_32x32x16_bf16 v[98:113], v[138:141], v[158:161], v[98:113]
	ds_read_b128 v[138:141], v166 offset:40960
	s_waitcnt lgkmcnt(3)
	v_mfma_f32_32x32x16_bf16 v[82:97], v[142:145], v[158:161], v[82:97]
	ds_read_b128 v[142:145], v166 offset:45056
	s_waitcnt lgkmcnt(3)
	v_mfma_f32_32x32x16_bf16 v[2:17], v[130:133], v[114:117], v[2:17]
	ds_read_b128 v[130:133], v167 offset:32768
	s_waitcnt lgkmcnt(3)
	v_mfma_f32_32x32x16_bf16 v[50:65], v[134:137], v[114:117], v[50:65]
	ds_read_b128 v[134:137], v167 offset:36864
	s_waitcnt lgkmcnt(3)
	v_mfma_f32_32x32x16_bf16 v[34:49], v[138:141], v[114:117], v[34:49]
	ds_read_b128 v[138:141], v167 offset:40960
	s_waitcnt lgkmcnt(3)
	v_mfma_f32_32x32x16_bf16 v[18:33], v[142:145], v[114:117], v[18:33]
	ds_read_b128 v[142:145], v167 offset:45056
	s_waitcnt lgkmcnt(3)
	v_mfma_f32_32x32x16_bf16 v[2:17], v[130:133], v[118:121], v[2:17]
	ds_read_b128 v[130:133], v168 offset:32768
	s_waitcnt lgkmcnt(3)
	v_mfma_f32_32x32x16_bf16 v[50:65], v[134:137], v[118:121], v[50:65]
	ds_read_b128 v[134:137], v168 offset:36864
	s_waitcnt lgkmcnt(3)
	v_mfma_f32_32x32x16_bf16 v[34:49], v[138:141], v[118:121], v[34:49]
	ds_read_b128 v[138:141], v168 offset:40960
	s_waitcnt lgkmcnt(3)
	v_mfma_f32_32x32x16_bf16 v[18:33], v[142:145], v[118:121], v[18:33]
	ds_read_b128 v[142:145], v168 offset:45056
	s_waitcnt lgkmcnt(3)
	v_mfma_f32_32x32x16_bf16 v[2:17], v[130:133], v[122:125], v[2:17]
	ds_read_b128 v[130:133], v169 offset:32768
	s_waitcnt lgkmcnt(3)
	v_mfma_f32_32x32x16_bf16 v[50:65], v[134:137], v[122:125], v[50:65]
	ds_read_b128 v[134:137], v169 offset:36864
	s_waitcnt lgkmcnt(3)
	v_mfma_f32_32x32x16_bf16 v[34:49], v[138:141], v[122:125], v[34:49]
	ds_read_b128 v[138:141], v169 offset:40960
	s_waitcnt lgkmcnt(3)
	v_mfma_f32_32x32x16_bf16 v[18:33], v[142:145], v[122:125], v[18:33]
	ds_read_b128 v[142:145], v169 offset:45056
	s_waitcnt lgkmcnt(3)
	v_mfma_f32_32x32x16_bf16 v[2:17], v[130:133], v[126:129], v[2:17]
	s_waitcnt lgkmcnt(2)
	v_mfma_f32_32x32x16_bf16 v[50:65], v[134:137], v[126:129], v[50:65]
	s_waitcnt lgkmcnt(1)
	v_mfma_f32_32x32x16_bf16 v[34:49], v[138:141], v[126:129], v[34:49]
	s_waitcnt lgkmcnt(0)
	v_mfma_f32_32x32x16_bf16 v[18:33], v[142:145], v[126:129], v[18:33]
	s_setprio 0
	s_addk_i32 s5, 0x4000
	s_and_b32 s0, s5, 0x4000
	v_add_u32_e32 v196, s0, v211
	v_lshl_add_u32 v221, s11, 14, v216
	v_add_u32_e32 v162, v196, v212
	v_add_u32_e32 v163, v196, v213
	v_add_u32_e32 v164, v196, v214
	v_add_u32_e32 v165, v196, v215
	v_add_u32_e32 v166, v221, v217
	v_add_u32_e32 v167, v221, v218
	v_add_u32_e32 v168, v221, v219
	v_add_u32_e32 v169, v221, v220
	ds_read_b128 v[130:133], v162
	ds_read_b128 v[134:137], v162 offset:4096
	ds_read_b128 v[138:141], v163
	ds_read_b128 v[142:145], v163 offset:4096
	s_mov_b64 s[6:7], 0
	s_mov_b64 s[8:9], 0

.Ldv_mid_fast:
	v_cvt_pk_bf16_f32 v114, v238, v239
	v_cvt_pk_bf16_f32 v115, v240, v241
	v_cvt_pk_bf16_f32 v116, v242, v243
	v_cvt_pk_bf16_f32 v117, v244, v245
	v_cvt_pk_bf16_f32 v118, v246, v247
	v_cvt_pk_bf16_f32 v119, v248, v249
	v_cvt_pk_bf16_f32 v120, v180, v181
	v_cvt_pk_bf16_f32 v121, v182, v183
	v_cvt_pk_bf16_f32 v122, v222, v223
	v_cvt_pk_bf16_f32 v123, v224, v225
	v_cvt_pk_bf16_f32 v124, v226, v227
	v_cvt_pk_bf16_f32 v125, v228, v229
	v_cvt_pk_bf16_f32 v126, v230, v231
	v_cvt_pk_bf16_f32 v127, v232, v233
	v_cvt_pk_bf16_f32 v128, v234, v235
	v_cvt_pk_bf16_f32 v129, v236, v237
	v_add_f32_e32 v197, v197, v199
	s_cmp_ge_u32 s41, s30
	s_cbranch_scc1 .Ldv_skip1
	s_and_b32 s0, s40, 0x8000
	s_add_i32 s0, s28, s0
	v_lshl_add_u64 v[198:199], s[84:85], 0, v[192:193]
	s_add_i32 m0, s0, 0x8000
	v_lshl_add_u64 v[198:199], v[198:199], 0, s[78:79]
	global_load_lds_dwordx4 v[198:199], off
	s_add_i32 m0, s0, 0xa000
	v_lshl_add_u64 v[198:199], s[84:85], 0, v[190:191]
	v_lshl_add_u64 v[198:199], v[198:199], 0, s[78:79]
	global_load_lds_dwordx4 v[198:199], off

.Ldv_skip2:
	s_setprio 1
	s_waitcnt lgkmcnt(3)
	v_mfma_f32_32x32x16_bf16 v[98:113], v[130:133], v[146:149], v[66:81]
	ds_read_b128 v[130:133], v164
	s_waitcnt lgkmcnt(3)
	v_mfma_f32_32x32x16_bf16 v[82:97], v[134:137], v[146:149], v[66:81]
	ds_read_b128 v[134:137], v164 offset:4096
	s_waitcnt lgkmcnt(3)
	v_mfma_f32_32x32x16_bf16 v[98:113], v[138:141], v[150:153], v[98:113]
	ds_read_b128 v[138:141], v165
	s_waitcnt lgkmcnt(3)
	v_mfma_f32_32x32x16_bf16 v[82:97], v[142:145], v[150:153], v[82:97]
	ds_read_b128 v[142:145], v165 offset:4096
	s_waitcnt lgkmcnt(3)
	v_mfma_f32_32x32x16_bf16 v[98:113], v[130:133], v[154:157], v[98:113]
	ds_read_b128 v[130:133], v166 offset:32768
	s_waitcnt lgkmcnt(3)
	v_mfma_f32_32x32x16_bf16 v[82:97], v[134:137], v[154:157], v[82:97]
	ds_read_b128 v[134:137], v166 offset:36864
	s_waitcnt lgkmcnt(3)
	v_mfma_f32_32x32x16_bf16 v[98:113], v[138:141], v[158:161], v[98:113]
	ds_read_b128 v[138:141], v166 offset:40960
	s_waitcnt lgkmcnt(3)
	v_mfma_f32_32x32x16_bf16 v[82:97], v[142:145], v[158:161], v[82:97]
	ds_read_b128 v[142:145], v166 offset:45056
	s_waitcnt lgkmcnt(3)
	v_mfma_f32_32x32x16_bf16 v[2:17], v[130:133], v[114:117], v[2:17]
	ds_read_b128 v[130:133], v167 offset:32768
	s_waitcnt lgkmcnt(3)
	v_mfma_f32_32x32x16_bf16 v[50:65], v[134:137], v[114:117], v[50:65]
	ds_read_b128 v[134:137], v167 offset:36864
	s_waitcnt lgkmcnt(3)
	v_mfma_f32_32x32x16_bf16 v[34:49], v[138:141], v[114:117], v[34:49]
	ds_read_b128 v[138:141], v167 offset:40960
	s_waitcnt lgkmcnt(3)
	v_mfma_f32_32x32x16_bf16 v[18:33], v[142:145], v[114:117], v[18:33]
	ds_read_b128 v[142:145], v167 offset:45056
	s_waitcnt lgkmcnt(3)
	v_mfma_f32_32x32x16_bf16 v[2:17], v[130:133], v[118:121], v[2:17]
	ds_read_b128 v[130:133], v168 offset:32768
	s_waitcnt lgkmcnt(3)
	v_mfma_f32_32x32x16_bf16 v[50:65], v[134:137], v[118:121], v[50:65]
	ds_read_b128 v[134:137], v168 offset:36864
	s_waitcnt lgkmcnt(3)
	v_mfma_f32_32x32x16_bf16 v[34:49], v[138:141], v[118:121], v[34:49]
	ds_read_b128 v[138:141], v168 offset:40960
	s_waitcnt lgkmcnt(3)
	v_mfma_f32_32x32x16_bf16 v[18:33], v[142:145], v[118:121], v[18:33]
	ds_read_b128 v[142:145], v168 offset:45056
	s_waitcnt lgkmcnt(3)
	v_mfma_f32_32x32x16_bf16 v[2:17], v[130:133], v[122:125], v[2:17]
	ds_read_b128 v[130:133], v169 offset:32768
	s_waitcnt lgkmcnt(3)
	v_mfma_f32_32x32x16_bf16 v[50:65], v[134:137], v[122:125], v[50:65]
	ds_read_b128 v[134:137], v169 offset:36864
	s_waitcnt lgkmcnt(3)
	v_mfma_f32_32x32x16_bf16 v[34:49], v[138:141], v[122:125], v[34:49]
	ds_read_b128 v[138:141], v169 offset:40960
	s_waitcnt lgkmcnt(3)
	v_mfma_f32_32x32x16_bf16 v[18:33], v[142:145], v[122:125], v[18:33]
	ds_read_b128 v[142:145], v169 offset:45056
	s_waitcnt lgkmcnt(3)
	v_mfma_f32_32x32x16_bf16 v[2:17], v[130:133], v[126:129], v[2:17]
	s_waitcnt lgkmcnt(2)
	v_mfma_f32_32x32x16_bf16 v[50:65], v[134:137], v[126:129], v[50:65]
	s_waitcnt lgkmcnt(1)
	v_mfma_f32_32x32x16_bf16 v[34:49], v[138:141], v[126:129], v[34:49]
	s_waitcnt lgkmcnt(0)
	v_mfma_f32_32x32x16_bf16 v[18:33], v[142:145], v[126:129], v[18:33]
	s_setprio 0
	s_cmp_ge_u32 s41, s30
	s_cbranch_scc1 .Ldend_skip
	v_readlane_b32 s0, v252, 7
	s_cmpk_lt_u32 s0, 0x100
	s_cbranch_scc0 .Ldend_skip
	s_mov_b64 s[6:7], 0
	s_mov_b64 s[8:9], 0
